# scan consumer: y outputs combined over 8 steps (butterfly across lane pairs/quads) instead of 4, loads-first group prologue
# speedup vs baseline: 1.0740x; 1.0082x over previous
.LBB0_1332:
	s_ashr_i32 s0, s55, 7
	s_bfe_u32 s33, s55, 0x40003
	s_lshl_b32 s60, s0, 8
	s_and_b32 s58, s55, 3
	s_bfe_u32 s44, s55, 0x10002
	s_lshl_b32 s59, s33, 6
	s_add_i32 s54, s60, 0x4000
	s_lshl_b32 s67, s0, 13
	s_mov_b64 s[0:1], -1
	s_and_b64 vcc, exec, s[20:21]
	s_cbranch_vccz .LBB0_1361
	s_cmp_eq_u32 s44, 0
	s_cselect_b64 s[0:1], -1, 0
	s_cmp_lg_u32 s44, 0
	s_cselect_b64 s[2:3], -1, 0
	s_and_b64 s[14:15], s[0:1], exec
	v_readlane_b32 s14, v254, 44
	s_cselect_b32 s14, 0, s14
	s_add_u32 s14, s18, s14
	s_addc_u32 s15, s19, 0
	s_lshl_b32 s16, s59, 1
	s_add_u32 s14, s14, s16
	s_addc_u32 s15, s15, 0
	s_lshl_b32 s16, s58, 5
	s_add_u32 s14, s14, s16
	s_addc_u32 s15, s15, 0
	v_lshl_add_u64 v[68:69], v[60:61], 1, s[14:15]
	s_and_b64 s[14:15], s[0:1], exec
	s_movk_i32 s14, 0x400
	s_cselect_b32 s17, 0, -1
	s_cselect_b32 s16, s14, 0xfffffc00
	v_mov_b32_e32 v0, 0
	s_mov_b32 s61, 0
	s_lshl_b64 s[14:15], s[16:17], 3
	s_add_i32 s62, s67, 0x20ff
	s_add_i32 s63, s67, 0xffffff00
	s_add_i32 s64, s60, 0x40ff
	v_and_b32_e32 v107, 15, v162
	v_bfrev_b32_e32 v109, v107
	v_lshrrev_b32_e32 v109, 29, v109
	v_cmp_gt_u32_e64 s[58:59], 8, v107
	v_mul_i32_i24_e32 v108, s16, v109
	v_lshlrev_b32_e32 v108, 1, v108
	v_ashrrev_i32_e32 v109, 31, v108
	s_mov_b32 s65, 0
	v_mov_b32_e32 v1, v0
	v_mov_b32_e32 v2, v0
	v_mov_b32_e32 v3, v0
	s_waitcnt vmcnt(0)
	s_barrier
	s_branch .LBB0_1335

.LBB0_1335:
	s_and_b32 s17, s61, 32
	s_mulk_i32 s17, 0x540
	s_add_i32 s56, s91, s17
	v_lshl_add_u32 v67, v77, 2, s56
	v_lshl_add_u32 v85, v60, 2, s56
	ds_read_b128 v[4:7], v67
	ds_read_b128 v[12:15], v67 offset:512
	ds_read_b128 v[8:11], v67 offset:256
	ds_read_b128 v[20:23], v67 offset:1024
	ds_read_b32 v74, v85 offset:1280
	ds_read_b128 v[24:27], v67 offset:1344
	ds_read_b128 v[32:35], v67 offset:1856
	ds_read_b128 v[28:31], v67 offset:1600
	ds_read_b128 v[40:43], v67 offset:2368
	ds_read_b32 v76, v85 offset:2624
	s_lshl_b32 s17, s65, 5
	s_sub_i32 s57, s62, s17
	s_cmp_gt_u32 s65, 7
	s_cselect_b32 s57, s57, s64
	s_cselect_b32 s16, s63, s54
	s_add_i32 s16, s16, s17
	s_cmp_lg_u64 s[2:3], 0
	s_cselect_b32 s16, s57, s16
	s_ashr_i32 s17, s16, 31
	s_lshl_b64 s[16:17], s[16:17], 11
	v_lshl_add_u64 v[72:73], v[68:69], 0, s[16:17]
	v_lshl_add_u64 v[72:73], v[72:73], 0, v[108:109]
	s_waitcnt lgkmcnt(5)
	v_pk_mul_f32 v[90:91], v[0:1], v[4:5]
	v_pk_fma_f32 v[86:87], v[12:13], v[74:75], v[0:1] op_sel_hi:[1,0,1]
	v_pk_fma_f32 v[90:91], v[2:3], v[6:7], v[90:91]
	ds_read_b128 v[44:47], v67 offset:2688
	v_pk_fma_f32 v[88:89], v[14:15], v[74:75], v[2:3] op_sel_hi:[1,0,1]
	v_add_f32_e32 v92, v90, v91
	ds_read_b128 v[52:55], v67 offset:3200
	ds_read_b128 v[48:51], v67 offset:2944
	v_add_f32_dpp v92, v92, v92 quad_perm:[1,0,3,2] row_mask:0xf bank_mask:0xf bound_ctrl:1
	ds_read_b128 v[80:83], v67 offset:3712
	ds_read_b32 v78, v85 offset:3968
	v_add_f32_dpp v92, v92, v92 quad_perm:[2,3,0,1] row_mask:0xf bank_mask:0xf bound_ctrl:1
	s_nop 1
	v_add_f32_dpp v92, v92, v92 row_half_mirror row_mask:0xf bank_mask:0xf bound_ctrl:1
	s_nop 1
	v_add_f32_dpp v92, v92, v92 row_mirror row_mask:0xf bank_mask:0xf bound_ctrl:1
	v_pk_fma_f32 v[0:1], v[8:9], v[92:93], v[86:87] op_sel_hi:[1,0,1]
	v_pk_fma_f32 v[2:3], v[10:11], v[92:93], v[88:89] op_sel_hi:[1,0,1]
	s_waitcnt lgkmcnt(5)
	v_pk_mul_f32 v[90:91], v[0:1], v[24:25]
	v_pk_fma_f32 v[86:87], v[32:33], v[76:77], v[0:1] op_sel_hi:[1,0,1]
	v_pk_fma_f32 v[90:91], v[2:3], v[26:27], v[90:91]
	v_pk_mul_f32 v[94:95], v[0:1], v[20:21]
	v_pk_fma_f32 v[88:89], v[34:35], v[76:77], v[2:3] op_sel_hi:[1,0,1]
	v_add_f32_e32 v92, v90, v91
	v_pk_fma_f32 v[94:95], v[2:3], v[22:23], v[94:95]
	ds_read_b128 v[4:7], v67 offset:4032
	v_add_f32_dpp v92, v92, v92 quad_perm:[1,0,3,2] row_mask:0xf bank_mask:0xf bound_ctrl:1
	ds_read_b128 v[12:15], v67 offset:4544
	ds_read_b128 v[8:11], v67 offset:4288
	v_add_f32_dpp v92, v92, v92 quad_perm:[2,3,0,1] row_mask:0xf bank_mask:0xf bound_ctrl:1
	ds_read_b128 v[20:23], v67 offset:5056
	ds_read_b32 v74, v85 offset:5312
	v_add_f32_dpp v92, v92, v92 row_half_mirror row_mask:0xf bank_mask:0xf bound_ctrl:1
	v_add_f32_e32 v96, v94, v95
	s_nop 0
	v_add_f32_dpp v92, v92, v92 row_mirror row_mask:0xf bank_mask:0xf bound_ctrl:1
	v_pk_fma_f32 v[0:1], v[28:29], v[92:93], v[86:87] op_sel_hi:[1,0,1]
	v_pk_fma_f32 v[2:3], v[30:31], v[92:93], v[88:89] op_sel_hi:[1,0,1]
	s_waitcnt lgkmcnt(5)
	v_pk_mul_f32 v[90:91], v[0:1], v[44:45]
	v_pk_fma_f32 v[86:87], v[52:53], v[78:79], v[0:1] op_sel_hi:[1,0,1]
	v_pk_fma_f32 v[90:91], v[2:3], v[46:47], v[90:91]
	v_pk_mul_f32 v[94:95], v[0:1], v[40:41]
	v_pk_fma_f32 v[88:89], v[54:55], v[78:79], v[2:3] op_sel_hi:[1,0,1]
	v_add_f32_e32 v92, v90, v91
	v_pk_fma_f32 v[94:95], v[2:3], v[42:43], v[94:95]
	ds_read_b128 v[24:27], v67 offset:5376
	v_add_f32_dpp v92, v92, v92 quad_perm:[1,0,3,2] row_mask:0xf bank_mask:0xf bound_ctrl:1
	ds_read_b128 v[32:35], v67 offset:5888
	ds_read_b128 v[28:31], v67 offset:5632
	v_add_f32_dpp v92, v92, v92 quad_perm:[2,3,0,1] row_mask:0xf bank_mask:0xf bound_ctrl:1
	ds_read_b128 v[40:43], v67 offset:6400
	ds_read_b32 v76, v85 offset:6656
	v_add_f32_dpp v92, v92, v92 row_half_mirror row_mask:0xf bank_mask:0xf bound_ctrl:1
	v_add_f32_e32 v97, v94, v95
	s_nop 0
	v_add_f32_dpp v92, v92, v92 row_mirror row_mask:0xf bank_mask:0xf bound_ctrl:1
	v_pk_fma_f32 v[0:1], v[48:49], v[92:93], v[86:87] op_sel_hi:[1,0,1]
	v_pk_fma_f32 v[2:3], v[50:51], v[92:93], v[88:89] op_sel_hi:[1,0,1]
	s_waitcnt lgkmcnt(5)
	v_pk_mul_f32 v[90:91], v[0:1], v[4:5]
	v_pk_fma_f32 v[86:87], v[12:13], v[74:75], v[0:1] op_sel_hi:[1,0,1]
	v_pk_fma_f32 v[90:91], v[2:3], v[6:7], v[90:91]
	v_pk_mul_f32 v[94:95], v[0:1], v[80:81]
	v_pk_fma_f32 v[88:89], v[14:15], v[74:75], v[2:3] op_sel_hi:[1,0,1]
	v_add_f32_e32 v92, v90, v91
	v_pk_fma_f32 v[94:95], v[2:3], v[82:83], v[94:95]
	ds_read_b128 v[44:47], v67 offset:6720
	v_add_f32_dpp v92, v92, v92 quad_perm:[1,0,3,2] row_mask:0xf bank_mask:0xf bound_ctrl:1
	ds_read_b128 v[52:55], v67 offset:7232
	ds_read_b128 v[48:51], v67 offset:6976
	v_add_f32_dpp v92, v92, v92 quad_perm:[2,3,0,1] row_mask:0xf bank_mask:0xf bound_ctrl:1
	ds_read_b128 v[80:83], v67 offset:7744
	ds_read_b32 v78, v85 offset:8000
	v_add_f32_dpp v92, v92, v92 row_half_mirror row_mask:0xf bank_mask:0xf bound_ctrl:1
	v_add_f32_e32 v98, v94, v95
	s_nop 0
	v_add_f32_dpp v92, v92, v92 row_mirror row_mask:0xf bank_mask:0xf bound_ctrl:1
	v_pk_fma_f32 v[0:1], v[8:9], v[92:93], v[86:87] op_sel_hi:[1,0,1]
	v_pk_fma_f32 v[2:3], v[10:11], v[92:93], v[88:89] op_sel_hi:[1,0,1]
	s_waitcnt lgkmcnt(5)
	v_pk_mul_f32 v[90:91], v[0:1], v[24:25]
	v_pk_fma_f32 v[86:87], v[32:33], v[76:77], v[0:1] op_sel_hi:[1,0,1]
	v_pk_fma_f32 v[90:91], v[2:3], v[26:27], v[90:91]
	v_pk_mul_f32 v[94:95], v[0:1], v[20:21]
	v_pk_fma_f32 v[88:89], v[34:35], v[76:77], v[2:3] op_sel_hi:[1,0,1]
	v_add_f32_e32 v92, v90, v91
	v_pk_fma_f32 v[94:95], v[2:3], v[22:23], v[94:95]
	ds_read_b128 v[4:7], v67 offset:8064
	v_add_f32_dpp v92, v92, v92 quad_perm:[1,0,3,2] row_mask:0xf bank_mask:0xf bound_ctrl:1
	ds_read_b128 v[12:15], v67 offset:8576
	ds_read_b128 v[8:11], v67 offset:8320
	v_add_f32_dpp v92, v92, v92 quad_perm:[2,3,0,1] row_mask:0xf bank_mask:0xf bound_ctrl:1
	ds_read_b128 v[20:23], v67 offset:9088
	ds_read_b32 v74, v85 offset:9344
	v_add_f32_dpp v92, v92, v92 row_half_mirror row_mask:0xf bank_mask:0xf bound_ctrl:1
	v_add_f32_e32 v99, v94, v95
	s_nop 0
	v_add_f32_dpp v92, v92, v92 row_mirror row_mask:0xf bank_mask:0xf bound_ctrl:1
	v_pk_fma_f32 v[0:1], v[28:29], v[92:93], v[86:87] op_sel_hi:[1,0,1]
	v_pk_fma_f32 v[2:3], v[30:31], v[92:93], v[88:89] op_sel_hi:[1,0,1]
	s_waitcnt lgkmcnt(5)
	v_pk_mul_f32 v[90:91], v[0:1], v[44:45]
	v_pk_fma_f32 v[86:87], v[52:53], v[78:79], v[0:1] op_sel_hi:[1,0,1]
	v_pk_fma_f32 v[90:91], v[2:3], v[46:47], v[90:91]
	v_pk_mul_f32 v[94:95], v[0:1], v[40:41]
	v_pk_fma_f32 v[88:89], v[54:55], v[78:79], v[2:3] op_sel_hi:[1,0,1]
	v_add_f32_e32 v92, v90, v91
	v_pk_fma_f32 v[94:95], v[2:3], v[42:43], v[94:95]
	ds_read_b128 v[24:27], v67 offset:9408
	v_add_f32_dpp v92, v92, v92 quad_perm:[1,0,3,2] row_mask:0xf bank_mask:0xf bound_ctrl:1
	ds_read_b128 v[32:35], v67 offset:9920
	ds_read_b128 v[28:31], v67 offset:9664
	v_add_f32_dpp v92, v92, v92 quad_perm:[2,3,0,1] row_mask:0xf bank_mask:0xf bound_ctrl:1
	ds_read_b128 v[40:43], v67 offset:10432
	ds_read_b32 v76, v85 offset:10688
	v_add_f32_dpp v92, v92, v92 row_half_mirror row_mask:0xf bank_mask:0xf bound_ctrl:1
	v_add_f32_e32 v100, v94, v95
	ds_read_b128 v[16:19], v67 offset:10176
	v_add_f32_dpp v92, v92, v92 row_mirror row_mask:0xf bank_mask:0xf bound_ctrl:1
	v_cndmask_b32_e64 v58, v96, v100, s[6:7]
	v_pk_fma_f32 v[0:1], v[48:49], v[92:93], v[86:87] op_sel_hi:[1,0,1]
	v_pk_fma_f32 v[2:3], v[50:51], v[92:93], v[88:89] op_sel_hi:[1,0,1]
	v_cndmask_b32_e64 v36, v100, v96, s[6:7]
	s_nop 1
	v_add_f32_dpp v36, v58, v36 quad_perm:[1,0,3,2] row_mask:0xf bank_mask:0xf bound_ctrl:1
	s_waitcnt lgkmcnt(6)
	v_pk_mul_f32 v[90:91], v[0:1], v[4:5]
	v_pk_fma_f32 v[86:87], v[12:13], v[74:75], v[0:1] op_sel_hi:[1,0,1]
	v_pk_fma_f32 v[90:91], v[2:3], v[6:7], v[90:91]
	v_pk_mul_f32 v[94:95], v[0:1], v[80:81]
	v_pk_fma_f32 v[88:89], v[14:15], v[74:75], v[2:3] op_sel_hi:[1,0,1]
	v_add_f32_e32 v92, v90, v91
	v_pk_fma_f32 v[94:95], v[2:3], v[82:83], v[94:95]
	ds_read_b128 v[44:47], v67 offset:10752
	v_add_f32_dpp v92, v92, v92 quad_perm:[1,0,3,2] row_mask:0xf bank_mask:0xf bound_ctrl:1
	ds_read_b128 v[52:55], v67 offset:11264
	ds_read_b128 v[48:51], v67 offset:11008
	v_add_f32_dpp v92, v92, v92 quad_perm:[2,3,0,1] row_mask:0xf bank_mask:0xf bound_ctrl:1
	ds_read_b128 v[80:83], v67 offset:11776
	ds_read_b32 v78, v85 offset:12032
	v_add_f32_dpp v92, v92, v92 row_half_mirror row_mask:0xf bank_mask:0xf bound_ctrl:1
	v_add_f32_e32 v101, v94, v95
	v_cndmask_b32_e64 v58, v97, v101, s[6:7]
	v_add_f32_dpp v92, v92, v92 row_mirror row_mask:0xf bank_mask:0xf bound_ctrl:1
	v_cndmask_b32_e64 v37, v101, v97, s[6:7]
	v_pk_fma_f32 v[0:1], v[8:9], v[92:93], v[86:87] op_sel_hi:[1,0,1]
	v_pk_fma_f32 v[2:3], v[10:11], v[92:93], v[88:89] op_sel_hi:[1,0,1]
	v_add_f32_dpp v37, v58, v37 quad_perm:[1,0,3,2] row_mask:0xf bank_mask:0xf bound_ctrl:1
	s_waitcnt lgkmcnt(5)
	v_pk_mul_f32 v[90:91], v[0:1], v[24:25]
	v_pk_fma_f32 v[86:87], v[32:33], v[76:77], v[0:1] op_sel_hi:[1,0,1]
	v_pk_fma_f32 v[90:91], v[2:3], v[26:27], v[90:91]
	v_pk_mul_f32 v[94:95], v[0:1], v[20:21]
	v_pk_fma_f32 v[88:89], v[34:35], v[76:77], v[2:3] op_sel_hi:[1,0,1]
	v_add_f32_e32 v92, v90, v91
	v_pk_fma_f32 v[94:95], v[2:3], v[22:23], v[94:95]
	ds_read_b128 v[4:7], v67 offset:12096
	v_add_f32_dpp v92, v92, v92 quad_perm:[1,0,3,2] row_mask:0xf bank_mask:0xf bound_ctrl:1
	ds_read_b128 v[12:15], v67 offset:12608
	ds_read_b128 v[8:11], v67 offset:12352
	v_add_f32_dpp v92, v92, v92 quad_perm:[2,3,0,1] row_mask:0xf bank_mask:0xf bound_ctrl:1
	ds_read_b128 v[20:23], v67 offset:13120
	ds_read_b32 v74, v85 offset:13376
	v_add_f32_dpp v92, v92, v92 row_half_mirror row_mask:0xf bank_mask:0xf bound_ctrl:1
	v_add_f32_e32 v102, v94, v95
	v_cndmask_b32_e64 v58, v98, v102, s[6:7]
	v_add_f32_dpp v92, v92, v92 row_mirror row_mask:0xf bank_mask:0xf bound_ctrl:1
	v_cndmask_b32_e64 v38, v102, v98, s[6:7]
	v_pk_fma_f32 v[0:1], v[28:29], v[92:93], v[86:87] op_sel_hi:[1,0,1]
	v_pk_fma_f32 v[2:3], v[30:31], v[92:93], v[88:89] op_sel_hi:[1,0,1]
	v_add_f32_dpp v38, v58, v38 quad_perm:[1,0,3,2] row_mask:0xf bank_mask:0xf bound_ctrl:1
	s_waitcnt lgkmcnt(5)
	v_pk_mul_f32 v[94:95], v[0:1], v[40:41]
	v_pk_fma_f32 v[94:95], v[2:3], v[42:43], v[94:95]
	v_pk_mul_f32 v[0:1], v[0:1], v[16:17]
	v_pk_mul_f32 v[2:3], v[2:3], v[18:19]
	ds_read_b128 v[24:27], v67 offset:13440
	v_pk_mul_f32 v[90:91], v[0:1], v[44:45]
	v_pk_fma_f32 v[86:87], v[52:53], v[78:79], v[0:1] op_sel_hi:[1,0,1]
	v_pk_fma_f32 v[90:91], v[2:3], v[46:47], v[90:91]
	ds_read_b128 v[32:35], v67 offset:13952
	v_pk_fma_f32 v[88:89], v[54:55], v[78:79], v[2:3] op_sel_hi:[1,0,1]
	v_add_f32_e32 v92, v90, v91
	ds_read_b128 v[28:31], v67 offset:13696
	ds_read_b128 v[40:43], v67 offset:14464
	v_add_f32_dpp v92, v92, v92 quad_perm:[1,0,3,2] row_mask:0xf bank_mask:0xf bound_ctrl:1
	ds_read_b32 v76, v85 offset:14720
	s_nop 0
	v_add_f32_dpp v92, v92, v92 quad_perm:[2,3,0,1] row_mask:0xf bank_mask:0xf bound_ctrl:1
	s_nop 1
	v_add_f32_dpp v92, v92, v92 row_half_mirror row_mask:0xf bank_mask:0xf bound_ctrl:1
	v_add_f32_e32 v103, v94, v95
	v_cndmask_b32_e64 v58, v99, v103, s[6:7]
	v_add_f32_dpp v92, v92, v92 row_mirror row_mask:0xf bank_mask:0xf bound_ctrl:1
	v_cndmask_b32_e64 v39, v103, v99, s[6:7]
	v_pk_fma_f32 v[0:1], v[48:49], v[92:93], v[86:87] op_sel_hi:[1,0,1]
	v_pk_fma_f32 v[2:3], v[50:51], v[92:93], v[88:89] op_sel_hi:[1,0,1]
	v_add_f32_dpp v39, v58, v39 quad_perm:[1,0,3,2] row_mask:0xf bank_mask:0xf bound_ctrl:1
	v_cndmask_b32_e64 v59, v36, v38, s[8:9]
	v_cndmask_b32_e64 v56, v38, v36, s[8:9]
	s_nop 1
	v_add_f32_dpp v56, v59, v56 quad_perm:[2,3,0,1] row_mask:0xf bank_mask:0xf bound_ctrl:1
	s_waitcnt lgkmcnt(5)
	v_pk_mul_f32 v[90:91], v[0:1], v[4:5]
	v_pk_fma_f32 v[86:87], v[12:13], v[74:75], v[0:1] op_sel_hi:[1,0,1]
	v_pk_fma_f32 v[90:91], v[2:3], v[6:7], v[90:91]
	v_pk_mul_f32 v[94:95], v[0:1], v[80:81]
	v_pk_fma_f32 v[88:89], v[14:15], v[74:75], v[2:3] op_sel_hi:[1,0,1]
	v_add_f32_e32 v92, v90, v91
	v_pk_fma_f32 v[94:95], v[2:3], v[82:83], v[94:95]
	ds_read_b128 v[44:47], v67 offset:14784
	v_add_f32_dpp v92, v92, v92 quad_perm:[1,0,3,2] row_mask:0xf bank_mask:0xf bound_ctrl:1
	ds_read_b128 v[52:55], v67 offset:15296
	ds_read_b128 v[48:51], v67 offset:15040
	v_add_f32_dpp v92, v92, v92 quad_perm:[2,3,0,1] row_mask:0xf bank_mask:0xf bound_ctrl:1
	ds_read_b128 v[80:83], v67 offset:15808
	ds_read_b32 v78, v85 offset:16064
	v_add_f32_dpp v92, v92, v92 row_half_mirror row_mask:0xf bank_mask:0xf bound_ctrl:1
	v_add_f32_e32 v96, v94, v95
	v_cndmask_b32_e64 v59, v37, v39, s[8:9]
	v_add_f32_dpp v92, v92, v92 row_mirror row_mask:0xf bank_mask:0xf bound_ctrl:1
	v_cndmask_b32_e64 v57, v39, v37, s[8:9]
	v_pk_fma_f32 v[0:1], v[8:9], v[92:93], v[86:87] op_sel_hi:[1,0,1]
	v_pk_fma_f32 v[2:3], v[10:11], v[92:93], v[88:89] op_sel_hi:[1,0,1]
	v_add_f32_dpp v57, v59, v57 quad_perm:[2,3,0,1] row_mask:0xf bank_mask:0xf bound_ctrl:1
	v_add_f32_dpp v56, v56, v56 row_ror:4 row_mask:0xf bank_mask:0xf bound_ctrl:1
	s_waitcnt lgkmcnt(5)
	v_pk_mul_f32 v[90:91], v[0:1], v[24:25]
	v_pk_fma_f32 v[86:87], v[32:33], v[76:77], v[0:1] op_sel_hi:[1,0,1]
	v_pk_fma_f32 v[90:91], v[2:3], v[26:27], v[90:91]
	v_pk_mul_f32 v[94:95], v[0:1], v[20:21]
	v_pk_fma_f32 v[88:89], v[34:35], v[76:77], v[2:3] op_sel_hi:[1,0,1]
	v_add_f32_e32 v92, v90, v91
	v_pk_fma_f32 v[94:95], v[2:3], v[22:23], v[94:95]
	ds_read_b128 v[4:7], v67 offset:16128
	v_add_f32_dpp v92, v92, v92 quad_perm:[1,0,3,2] row_mask:0xf bank_mask:0xf bound_ctrl:1
	ds_read_b128 v[12:15], v67 offset:16640
	ds_read_b128 v[8:11], v67 offset:16384
	v_add_f32_dpp v92, v92, v92 quad_perm:[2,3,0,1] row_mask:0xf bank_mask:0xf bound_ctrl:1
	ds_read_b128 v[20:23], v67 offset:17152
	ds_read_b32 v74, v85 offset:17408
	v_add_f32_dpp v92, v92, v92 row_half_mirror row_mask:0xf bank_mask:0xf bound_ctrl:1
	v_add_f32_e32 v97, v94, v95
	v_add_f32_dpp v56, v56, v56 row_ror:8 row_mask:0xf bank_mask:0xf bound_ctrl:1
	v_add_f32_dpp v92, v92, v92 row_mirror row_mask:0xf bank_mask:0xf bound_ctrl:1
	v_add_f32_dpp v57, v57, v57 row_ror:4 row_mask:0xf bank_mask:0xf bound_ctrl:1
	v_pk_fma_f32 v[0:1], v[28:29], v[92:93], v[86:87] op_sel_hi:[1,0,1]
	v_pk_fma_f32 v[2:3], v[30:31], v[92:93], v[88:89] op_sel_hi:[1,0,1]
	v_add_f32_dpp v57, v57, v57 row_ror:8 row_mask:0xf bank_mask:0xf bound_ctrl:1
	s_waitcnt lgkmcnt(5)
	v_pk_mul_f32 v[90:91], v[0:1], v[44:45]
	v_pk_fma_f32 v[86:87], v[52:53], v[78:79], v[0:1] op_sel_hi:[1,0,1]
	v_pk_fma_f32 v[90:91], v[2:3], v[46:47], v[90:91]
	v_pk_mul_f32 v[94:95], v[0:1], v[40:41]
	v_pk_fma_f32 v[88:89], v[54:55], v[78:79], v[2:3] op_sel_hi:[1,0,1]
	v_add_f32_e32 v92, v90, v91
	v_pk_fma_f32 v[94:95], v[2:3], v[42:43], v[94:95]
	ds_read_b128 v[24:27], v67 offset:17472
	v_add_f32_dpp v92, v92, v92 quad_perm:[1,0,3,2] row_mask:0xf bank_mask:0xf bound_ctrl:1
	ds_read_b128 v[32:35], v67 offset:17984
	ds_read_b128 v[28:31], v67 offset:17728
	v_add_f32_dpp v92, v92, v92 quad_perm:[2,3,0,1] row_mask:0xf bank_mask:0xf bound_ctrl:1
	ds_read_b128 v[40:43], v67 offset:18496
	ds_read_b32 v76, v85 offset:18752
	v_add_f32_dpp v92, v92, v92 row_half_mirror row_mask:0xf bank_mask:0xf bound_ctrl:1
	v_add_f32_e32 v98, v94, v95
	v_mov_b32_dpp v56, v57 quad_perm:[0,1,2,3] row_mask:0xf bank_mask:0x2
	v_add_f32_dpp v92, v92, v92 row_mirror row_mask:0xf bank_mask:0xf bound_ctrl:1
	v_cvt_pk_bf16_f32 v56, v56, v56
	v_pk_fma_f32 v[0:1], v[48:49], v[92:93], v[86:87] op_sel_hi:[1,0,1]
	v_pk_fma_f32 v[2:3], v[50:51], v[92:93], v[88:89] op_sel_hi:[1,0,1]
	s_and_saveexec_b64 s[16:17], s[58:59]
	global_store_short v[72:73], v56, off
	s_or_b64 exec, exec, s[16:17]
	v_lshl_add_u64 v[72:73], s[14:15], 1, v[72:73]
	s_waitcnt lgkmcnt(5)
	v_pk_mul_f32 v[90:91], v[0:1], v[4:5]
	v_pk_fma_f32 v[86:87], v[12:13], v[74:75], v[0:1] op_sel_hi:[1,0,1]
	v_pk_fma_f32 v[90:91], v[2:3], v[6:7], v[90:91]
	v_pk_mul_f32 v[94:95], v[0:1], v[80:81]
	v_pk_fma_f32 v[88:89], v[14:15], v[74:75], v[2:3] op_sel_hi:[1,0,1]
	v_add_f32_e32 v92, v90, v91
	v_pk_fma_f32 v[94:95], v[2:3], v[82:83], v[94:95]
	ds_read_b128 v[44:47], v67 offset:18816
	v_add_f32_dpp v92, v92, v92 quad_perm:[1,0,3,2] row_mask:0xf bank_mask:0xf bound_ctrl:1
	ds_read_b128 v[52:55], v67 offset:19328
	ds_read_b128 v[48:51], v67 offset:19072
	v_add_f32_dpp v92, v92, v92 quad_perm:[2,3,0,1] row_mask:0xf bank_mask:0xf bound_ctrl:1
	ds_read_b128 v[80:83], v67 offset:19840
	ds_read_b32 v78, v85 offset:20096
	v_add_f32_dpp v92, v92, v92 row_half_mirror row_mask:0xf bank_mask:0xf bound_ctrl:1
	v_add_f32_e32 v99, v94, v95
	s_nop 0
	v_add_f32_dpp v92, v92, v92 row_mirror row_mask:0xf bank_mask:0xf bound_ctrl:1
	v_pk_fma_f32 v[0:1], v[8:9], v[92:93], v[86:87] op_sel_hi:[1,0,1]
	v_pk_fma_f32 v[2:3], v[10:11], v[92:93], v[88:89] op_sel_hi:[1,0,1]
	s_waitcnt lgkmcnt(5)
	v_pk_mul_f32 v[90:91], v[0:1], v[24:25]
	v_pk_fma_f32 v[86:87], v[32:33], v[76:77], v[0:1] op_sel_hi:[1,0,1]
	v_pk_fma_f32 v[90:91], v[2:3], v[26:27], v[90:91]
	v_pk_mul_f32 v[94:95], v[0:1], v[20:21]
	v_pk_fma_f32 v[88:89], v[34:35], v[76:77], v[2:3] op_sel_hi:[1,0,1]
	v_add_f32_e32 v92, v90, v91
	v_pk_fma_f32 v[94:95], v[2:3], v[22:23], v[94:95]
	ds_read_b128 v[4:7], v67 offset:20160
	v_add_f32_dpp v92, v92, v92 quad_perm:[1,0,3,2] row_mask:0xf bank_mask:0xf bound_ctrl:1
	ds_read_b128 v[12:15], v67 offset:20672
	ds_read_b128 v[8:11], v67 offset:20416
	v_add_f32_dpp v92, v92, v92 quad_perm:[2,3,0,1] row_mask:0xf bank_mask:0xf bound_ctrl:1
	ds_read_b128 v[20:23], v67 offset:21184
	ds_read_b32 v74, v85 offset:21440
	v_add_f32_dpp v92, v92, v92 row_half_mirror row_mask:0xf bank_mask:0xf bound_ctrl:1
	v_add_f32_e32 v100, v94, v95
	ds_read_b128 v[16:19], v67 offset:20928
	v_add_f32_dpp v92, v92, v92 row_mirror row_mask:0xf bank_mask:0xf bound_ctrl:1
	v_cndmask_b32_e64 v58, v96, v100, s[6:7]
	v_pk_fma_f32 v[0:1], v[28:29], v[92:93], v[86:87] op_sel_hi:[1,0,1]
	v_pk_fma_f32 v[2:3], v[30:31], v[92:93], v[88:89] op_sel_hi:[1,0,1]
	v_cndmask_b32_e64 v36, v100, v96, s[6:7]
	s_nop 1
	v_add_f32_dpp v36, v58, v36 quad_perm:[1,0,3,2] row_mask:0xf bank_mask:0xf bound_ctrl:1
	s_waitcnt lgkmcnt(6)
	v_pk_mul_f32 v[90:91], v[0:1], v[44:45]
	v_pk_fma_f32 v[86:87], v[52:53], v[78:79], v[0:1] op_sel_hi:[1,0,1]
	v_pk_fma_f32 v[90:91], v[2:3], v[46:47], v[90:91]
	v_pk_mul_f32 v[94:95], v[0:1], v[40:41]
	v_pk_fma_f32 v[88:89], v[54:55], v[78:79], v[2:3] op_sel_hi:[1,0,1]
	v_add_f32_e32 v92, v90, v91
	v_pk_fma_f32 v[94:95], v[2:3], v[42:43], v[94:95]
	ds_read_b128 v[24:27], v67 offset:21504
	v_add_f32_dpp v92, v92, v92 quad_perm:[1,0,3,2] row_mask:0xf bank_mask:0xf bound_ctrl:1
	ds_read_b128 v[32:35], v67 offset:22016
	ds_read_b128 v[28:31], v67 offset:21760
	v_add_f32_dpp v92, v92, v92 quad_perm:[2,3,0,1] row_mask:0xf bank_mask:0xf bound_ctrl:1
	ds_read_b128 v[40:43], v67 offset:22528
	ds_read_b32 v76, v85 offset:22784
	v_add_f32_dpp v92, v92, v92 row_half_mirror row_mask:0xf bank_mask:0xf bound_ctrl:1
	v_add_f32_e32 v101, v94, v95
	v_cndmask_b32_e64 v58, v97, v101, s[6:7]
	v_add_f32_dpp v92, v92, v92 row_mirror row_mask:0xf bank_mask:0xf bound_ctrl:1
	v_cndmask_b32_e64 v37, v101, v97, s[6:7]
	v_pk_fma_f32 v[0:1], v[48:49], v[92:93], v[86:87] op_sel_hi:[1,0,1]
	v_pk_fma_f32 v[2:3], v[50:51], v[92:93], v[88:89] op_sel_hi:[1,0,1]
	v_add_f32_dpp v37, v58, v37 quad_perm:[1,0,3,2] row_mask:0xf bank_mask:0xf bound_ctrl:1
	s_waitcnt lgkmcnt(5)
	v_pk_mul_f32 v[90:91], v[0:1], v[4:5]
	v_pk_fma_f32 v[86:87], v[12:13], v[74:75], v[0:1] op_sel_hi:[1,0,1]
	v_pk_fma_f32 v[90:91], v[2:3], v[6:7], v[90:91]
	v_pk_mul_f32 v[94:95], v[0:1], v[80:81]
	v_pk_fma_f32 v[88:89], v[14:15], v[74:75], v[2:3] op_sel_hi:[1,0,1]
	v_add_f32_e32 v92, v90, v91
	v_pk_fma_f32 v[94:95], v[2:3], v[82:83], v[94:95]
	ds_read_b128 v[44:47], v67 offset:22848
	v_add_f32_dpp v92, v92, v92 quad_perm:[1,0,3,2] row_mask:0xf bank_mask:0xf bound_ctrl:1
	ds_read_b128 v[52:55], v67 offset:23360
	ds_read_b128 v[48:51], v67 offset:23104
	v_add_f32_dpp v92, v92, v92 quad_perm:[2,3,0,1] row_mask:0xf bank_mask:0xf bound_ctrl:1
	ds_read_b128 v[80:83], v67 offset:23872
	ds_read_b32 v78, v85 offset:24128
	v_add_f32_dpp v92, v92, v92 row_half_mirror row_mask:0xf bank_mask:0xf bound_ctrl:1
	v_add_f32_e32 v102, v94, v95
	v_cndmask_b32_e64 v58, v98, v102, s[6:7]
	v_add_f32_dpp v92, v92, v92 row_mirror row_mask:0xf bank_mask:0xf bound_ctrl:1
	v_cndmask_b32_e64 v38, v102, v98, s[6:7]
	v_pk_fma_f32 v[0:1], v[8:9], v[92:93], v[86:87] op_sel_hi:[1,0,1]
	v_pk_fma_f32 v[2:3], v[10:11], v[92:93], v[88:89] op_sel_hi:[1,0,1]
	v_add_f32_dpp v38, v58, v38 quad_perm:[1,0,3,2] row_mask:0xf bank_mask:0xf bound_ctrl:1
	s_waitcnt lgkmcnt(5)
	v_pk_mul_f32 v[94:95], v[0:1], v[20:21]
	v_pk_fma_f32 v[94:95], v[2:3], v[22:23], v[94:95]
	v_pk_mul_f32 v[0:1], v[0:1], v[16:17]
	v_pk_mul_f32 v[2:3], v[2:3], v[18:19]
	ds_read_b128 v[4:7], v67 offset:24192
	v_pk_mul_f32 v[90:91], v[0:1], v[24:25]
	v_pk_fma_f32 v[86:87], v[32:33], v[76:77], v[0:1] op_sel_hi:[1,0,1]
	v_pk_fma_f32 v[90:91], v[2:3], v[26:27], v[90:91]
	ds_read_b128 v[12:15], v67 offset:24704
	v_pk_fma_f32 v[88:89], v[34:35], v[76:77], v[2:3] op_sel_hi:[1,0,1]
	v_add_f32_e32 v92, v90, v91
	ds_read_b128 v[8:11], v67 offset:24448
	ds_read_b128 v[20:23], v67 offset:25216
	v_add_f32_dpp v92, v92, v92 quad_perm:[1,0,3,2] row_mask:0xf bank_mask:0xf bound_ctrl:1
	ds_read_b32 v74, v85 offset:25472
	s_nop 0
	v_add_f32_dpp v92, v92, v92 quad_perm:[2,3,0,1] row_mask:0xf bank_mask:0xf bound_ctrl:1
	s_nop 1
	v_add_f32_dpp v92, v92, v92 row_half_mirror row_mask:0xf bank_mask:0xf bound_ctrl:1
	v_add_f32_e32 v103, v94, v95
	v_cndmask_b32_e64 v58, v99, v103, s[6:7]
	v_add_f32_dpp v92, v92, v92 row_mirror row_mask:0xf bank_mask:0xf bound_ctrl:1
	v_cndmask_b32_e64 v39, v103, v99, s[6:7]
	v_pk_fma_f32 v[0:1], v[28:29], v[92:93], v[86:87] op_sel_hi:[1,0,1]
	v_pk_fma_f32 v[2:3], v[30:31], v[92:93], v[88:89] op_sel_hi:[1,0,1]
	v_add_f32_dpp v39, v58, v39 quad_perm:[1,0,3,2] row_mask:0xf bank_mask:0xf bound_ctrl:1
	v_cndmask_b32_e64 v59, v36, v38, s[8:9]
	v_cndmask_b32_e64 v56, v38, v36, s[8:9]
	s_nop 1
	v_add_f32_dpp v56, v59, v56 quad_perm:[2,3,0,1] row_mask:0xf bank_mask:0xf bound_ctrl:1
	s_waitcnt lgkmcnt(5)
	v_pk_mul_f32 v[90:91], v[0:1], v[44:45]
	v_pk_fma_f32 v[86:87], v[52:53], v[78:79], v[0:1] op_sel_hi:[1,0,1]
	v_pk_fma_f32 v[90:91], v[2:3], v[46:47], v[90:91]
	v_pk_mul_f32 v[94:95], v[0:1], v[40:41]
	v_pk_fma_f32 v[88:89], v[54:55], v[78:79], v[2:3] op_sel_hi:[1,0,1]
	v_add_f32_e32 v92, v90, v91
	v_pk_fma_f32 v[94:95], v[2:3], v[42:43], v[94:95]
	ds_read_b128 v[24:27], v67 offset:25536
	v_add_f32_dpp v92, v92, v92 quad_perm:[1,0,3,2] row_mask:0xf bank_mask:0xf bound_ctrl:1
	ds_read_b128 v[32:35], v67 offset:26048
	ds_read_b128 v[28:31], v67 offset:25792
	v_add_f32_dpp v92, v92, v92 quad_perm:[2,3,0,1] row_mask:0xf bank_mask:0xf bound_ctrl:1
	ds_read_b128 v[40:43], v67 offset:26560
	ds_read_b32 v76, v85 offset:26816
	v_add_f32_dpp v92, v92, v92 row_half_mirror row_mask:0xf bank_mask:0xf bound_ctrl:1
	v_add_f32_e32 v96, v94, v95
	v_cndmask_b32_e64 v59, v37, v39, s[8:9]
	v_add_f32_dpp v92, v92, v92 row_mirror row_mask:0xf bank_mask:0xf bound_ctrl:1
	v_cndmask_b32_e64 v57, v39, v37, s[8:9]
	v_pk_fma_f32 v[0:1], v[48:49], v[92:93], v[86:87] op_sel_hi:[1,0,1]
	v_pk_fma_f32 v[2:3], v[50:51], v[92:93], v[88:89] op_sel_hi:[1,0,1]
	v_add_f32_dpp v57, v59, v57 quad_perm:[2,3,0,1] row_mask:0xf bank_mask:0xf bound_ctrl:1
	v_add_f32_dpp v56, v56, v56 row_ror:4 row_mask:0xf bank_mask:0xf bound_ctrl:1
	s_waitcnt lgkmcnt(5)
	v_pk_mul_f32 v[90:91], v[0:1], v[4:5]
	v_pk_fma_f32 v[86:87], v[12:13], v[74:75], v[0:1] op_sel_hi:[1,0,1]
	v_pk_fma_f32 v[90:91], v[2:3], v[6:7], v[90:91]
	v_pk_mul_f32 v[94:95], v[0:1], v[80:81]
	v_pk_fma_f32 v[88:89], v[14:15], v[74:75], v[2:3] op_sel_hi:[1,0,1]
	v_add_f32_e32 v92, v90, v91
	v_pk_fma_f32 v[94:95], v[2:3], v[82:83], v[94:95]
	ds_read_b128 v[44:47], v67 offset:26880
	v_add_f32_dpp v92, v92, v92 quad_perm:[1,0,3,2] row_mask:0xf bank_mask:0xf bound_ctrl:1
	ds_read_b128 v[52:55], v67 offset:27392
	ds_read_b128 v[48:51], v67 offset:27136
	v_add_f32_dpp v92, v92, v92 quad_perm:[2,3,0,1] row_mask:0xf bank_mask:0xf bound_ctrl:1
	ds_read_b128 v[80:83], v67 offset:27904
	ds_read_b32 v78, v85 offset:28160
	v_add_f32_dpp v92, v92, v92 row_half_mirror row_mask:0xf bank_mask:0xf bound_ctrl:1
	v_add_f32_e32 v97, v94, v95
	v_add_f32_dpp v56, v56, v56 row_ror:8 row_mask:0xf bank_mask:0xf bound_ctrl:1
	v_add_f32_dpp v92, v92, v92 row_mirror row_mask:0xf bank_mask:0xf bound_ctrl:1
	v_add_f32_dpp v57, v57, v57 row_ror:4 row_mask:0xf bank_mask:0xf bound_ctrl:1
	v_pk_fma_f32 v[0:1], v[8:9], v[92:93], v[86:87] op_sel_hi:[1,0,1]
	v_pk_fma_f32 v[2:3], v[10:11], v[92:93], v[88:89] op_sel_hi:[1,0,1]
	v_add_f32_dpp v57, v57, v57 row_ror:8 row_mask:0xf bank_mask:0xf bound_ctrl:1
	s_waitcnt lgkmcnt(5)
	v_pk_mul_f32 v[90:91], v[0:1], v[24:25]
	v_pk_fma_f32 v[86:87], v[32:33], v[76:77], v[0:1] op_sel_hi:[1,0,1]
	v_pk_fma_f32 v[90:91], v[2:3], v[26:27], v[90:91]
	v_pk_mul_f32 v[94:95], v[0:1], v[20:21]
	v_pk_fma_f32 v[88:89], v[34:35], v[76:77], v[2:3] op_sel_hi:[1,0,1]
	v_add_f32_e32 v92, v90, v91
	v_pk_fma_f32 v[94:95], v[2:3], v[22:23], v[94:95]
	ds_read_b128 v[4:7], v67 offset:28224
	v_add_f32_dpp v92, v92, v92 quad_perm:[1,0,3,2] row_mask:0xf bank_mask:0xf bound_ctrl:1
	ds_read_b128 v[12:15], v67 offset:28736
	ds_read_b128 v[8:11], v67 offset:28480
	v_add_f32_dpp v92, v92, v92 quad_perm:[2,3,0,1] row_mask:0xf bank_mask:0xf bound_ctrl:1
	ds_read_b128 v[20:23], v67 offset:29248
	ds_read_b32 v74, v85 offset:29504
	v_add_f32_dpp v92, v92, v92 row_half_mirror row_mask:0xf bank_mask:0xf bound_ctrl:1
	v_add_f32_e32 v98, v94, v95
	v_mov_b32_dpp v56, v57 quad_perm:[0,1,2,3] row_mask:0xf bank_mask:0x2
	v_add_f32_dpp v92, v92, v92 row_mirror row_mask:0xf bank_mask:0xf bound_ctrl:1
	v_cvt_pk_bf16_f32 v56, v56, v56
	v_pk_fma_f32 v[0:1], v[28:29], v[92:93], v[86:87] op_sel_hi:[1,0,1]
	v_pk_fma_f32 v[2:3], v[30:31], v[92:93], v[88:89] op_sel_hi:[1,0,1]
	s_and_saveexec_b64 s[16:17], s[58:59]
	global_store_short v[72:73], v56, off
	s_or_b64 exec, exec, s[16:17]
	v_lshl_add_u64 v[72:73], s[14:15], 1, v[72:73]
	s_waitcnt lgkmcnt(5)
	v_pk_mul_f32 v[90:91], v[0:1], v[44:45]
	v_pk_fma_f32 v[86:87], v[52:53], v[78:79], v[0:1] op_sel_hi:[1,0,1]
	v_pk_fma_f32 v[90:91], v[2:3], v[46:47], v[90:91]
	v_pk_mul_f32 v[94:95], v[0:1], v[40:41]
	v_pk_fma_f32 v[88:89], v[54:55], v[78:79], v[2:3] op_sel_hi:[1,0,1]
	v_add_f32_e32 v92, v90, v91
	v_pk_fma_f32 v[94:95], v[2:3], v[42:43], v[94:95]
	ds_read_b128 v[24:27], v67 offset:29568
	v_add_f32_dpp v92, v92, v92 quad_perm:[1,0,3,2] row_mask:0xf bank_mask:0xf bound_ctrl:1
	ds_read_b128 v[32:35], v67 offset:30080
	ds_read_b128 v[28:31], v67 offset:29824
	v_add_f32_dpp v92, v92, v92 quad_perm:[2,3,0,1] row_mask:0xf bank_mask:0xf bound_ctrl:1
	ds_read_b128 v[40:43], v67 offset:30592
	ds_read_b32 v76, v85 offset:30848
	v_add_f32_dpp v92, v92, v92 row_half_mirror row_mask:0xf bank_mask:0xf bound_ctrl:1
	v_add_f32_e32 v99, v94, v95
	s_nop 0
	v_add_f32_dpp v92, v92, v92 row_mirror row_mask:0xf bank_mask:0xf bound_ctrl:1
	v_pk_fma_f32 v[0:1], v[48:49], v[92:93], v[86:87] op_sel_hi:[1,0,1]
	v_pk_fma_f32 v[2:3], v[50:51], v[92:93], v[88:89] op_sel_hi:[1,0,1]
	s_waitcnt lgkmcnt(5)
	v_pk_mul_f32 v[90:91], v[0:1], v[4:5]
	v_pk_fma_f32 v[86:87], v[12:13], v[74:75], v[0:1] op_sel_hi:[1,0,1]
	v_pk_fma_f32 v[90:91], v[2:3], v[6:7], v[90:91]
	v_pk_mul_f32 v[94:95], v[0:1], v[80:81]
	v_pk_fma_f32 v[88:89], v[14:15], v[74:75], v[2:3] op_sel_hi:[1,0,1]
	v_add_f32_e32 v92, v90, v91
	v_pk_fma_f32 v[94:95], v[2:3], v[82:83], v[94:95]
	ds_read_b128 v[44:47], v67 offset:30912
	v_add_f32_dpp v92, v92, v92 quad_perm:[1,0,3,2] row_mask:0xf bank_mask:0xf bound_ctrl:1
	ds_read_b128 v[52:55], v67 offset:31424
	ds_read_b128 v[48:51], v67 offset:31168
	v_add_f32_dpp v92, v92, v92 quad_perm:[2,3,0,1] row_mask:0xf bank_mask:0xf bound_ctrl:1
	ds_read_b128 v[80:83], v67 offset:31936
	ds_read_b32 v78, v85 offset:32192
	v_add_f32_dpp v92, v92, v92 row_half_mirror row_mask:0xf bank_mask:0xf bound_ctrl:1
	v_add_f32_e32 v100, v94, v95
	ds_read_b128 v[16:19], v67 offset:31680
	v_add_f32_dpp v92, v92, v92 row_mirror row_mask:0xf bank_mask:0xf bound_ctrl:1
	v_cndmask_b32_e64 v58, v96, v100, s[6:7]
	v_pk_fma_f32 v[0:1], v[8:9], v[92:93], v[86:87] op_sel_hi:[1,0,1]
	v_pk_fma_f32 v[2:3], v[10:11], v[92:93], v[88:89] op_sel_hi:[1,0,1]
	v_cndmask_b32_e64 v36, v100, v96, s[6:7]
	s_nop 1
	v_add_f32_dpp v36, v58, v36 quad_perm:[1,0,3,2] row_mask:0xf bank_mask:0xf bound_ctrl:1
	s_waitcnt lgkmcnt(6)
	v_pk_mul_f32 v[90:91], v[0:1], v[24:25]
	v_pk_fma_f32 v[86:87], v[32:33], v[76:77], v[0:1] op_sel_hi:[1,0,1]
	v_pk_fma_f32 v[90:91], v[2:3], v[26:27], v[90:91]
	v_pk_mul_f32 v[94:95], v[0:1], v[20:21]
	v_pk_fma_f32 v[88:89], v[34:35], v[76:77], v[2:3] op_sel_hi:[1,0,1]
	v_add_f32_e32 v92, v90, v91
	v_pk_fma_f32 v[94:95], v[2:3], v[22:23], v[94:95]
	ds_read_b128 v[4:7], v67 offset:32256
	v_add_f32_dpp v92, v92, v92 quad_perm:[1,0,3,2] row_mask:0xf bank_mask:0xf bound_ctrl:1
	ds_read_b128 v[12:15], v67 offset:32768
	ds_read_b128 v[8:11], v67 offset:32512
	v_add_f32_dpp v92, v92, v92 quad_perm:[2,3,0,1] row_mask:0xf bank_mask:0xf bound_ctrl:1
	ds_read_b128 v[20:23], v67 offset:33280
	ds_read_b32 v74, v85 offset:33536
	v_add_f32_dpp v92, v92, v92 row_half_mirror row_mask:0xf bank_mask:0xf bound_ctrl:1
	v_add_f32_e32 v101, v94, v95
	v_cndmask_b32_e64 v58, v97, v101, s[6:7]
	v_add_f32_dpp v92, v92, v92 row_mirror row_mask:0xf bank_mask:0xf bound_ctrl:1
	v_cndmask_b32_e64 v37, v101, v97, s[6:7]
	v_pk_fma_f32 v[0:1], v[28:29], v[92:93], v[86:87] op_sel_hi:[1,0,1]
	v_pk_fma_f32 v[2:3], v[30:31], v[92:93], v[88:89] op_sel_hi:[1,0,1]
	v_add_f32_dpp v37, v58, v37 quad_perm:[1,0,3,2] row_mask:0xf bank_mask:0xf bound_ctrl:1
	s_waitcnt lgkmcnt(5)
	v_pk_mul_f32 v[90:91], v[0:1], v[44:45]
	v_pk_fma_f32 v[86:87], v[52:53], v[78:79], v[0:1] op_sel_hi:[1,0,1]
	v_pk_fma_f32 v[90:91], v[2:3], v[46:47], v[90:91]
	v_pk_mul_f32 v[94:95], v[0:1], v[40:41]
	v_pk_fma_f32 v[88:89], v[54:55], v[78:79], v[2:3] op_sel_hi:[1,0,1]
	v_add_f32_e32 v92, v90, v91
	v_pk_fma_f32 v[94:95], v[2:3], v[42:43], v[94:95]
	ds_read_b128 v[24:27], v67 offset:33600
	v_add_f32_dpp v92, v92, v92 quad_perm:[1,0,3,2] row_mask:0xf bank_mask:0xf bound_ctrl:1
	ds_read_b128 v[32:35], v67 offset:34112
	ds_read_b128 v[28:31], v67 offset:33856
	v_add_f32_dpp v92, v92, v92 quad_perm:[2,3,0,1] row_mask:0xf bank_mask:0xf bound_ctrl:1
	ds_read_b128 v[40:43], v67 offset:34624
	ds_read_b32 v76, v85 offset:34880
	v_add_f32_dpp v92, v92, v92 row_half_mirror row_mask:0xf bank_mask:0xf bound_ctrl:1
	v_add_f32_e32 v102, v94, v95
	v_cndmask_b32_e64 v58, v98, v102, s[6:7]
	v_add_f32_dpp v92, v92, v92 row_mirror row_mask:0xf bank_mask:0xf bound_ctrl:1
	v_cndmask_b32_e64 v38, v102, v98, s[6:7]
	v_pk_fma_f32 v[0:1], v[48:49], v[92:93], v[86:87] op_sel_hi:[1,0,1]
	v_pk_fma_f32 v[2:3], v[50:51], v[92:93], v[88:89] op_sel_hi:[1,0,1]
	v_add_f32_dpp v38, v58, v38 quad_perm:[1,0,3,2] row_mask:0xf bank_mask:0xf bound_ctrl:1
	s_waitcnt lgkmcnt(5)
	v_pk_mul_f32 v[94:95], v[0:1], v[80:81]
	v_pk_fma_f32 v[94:95], v[2:3], v[82:83], v[94:95]
	v_pk_mul_f32 v[0:1], v[0:1], v[16:17]
	v_pk_mul_f32 v[2:3], v[2:3], v[18:19]
	ds_read_b128 v[44:47], v67 offset:34944
	v_pk_mul_f32 v[90:91], v[0:1], v[4:5]
	v_pk_fma_f32 v[86:87], v[12:13], v[74:75], v[0:1] op_sel_hi:[1,0,1]
	v_pk_fma_f32 v[90:91], v[2:3], v[6:7], v[90:91]
	ds_read_b128 v[52:55], v67 offset:35456
	v_pk_fma_f32 v[88:89], v[14:15], v[74:75], v[2:3] op_sel_hi:[1,0,1]
	v_add_f32_e32 v92, v90, v91
	ds_read_b128 v[48:51], v67 offset:35200
	ds_read_b128 v[80:83], v67 offset:35968
	v_add_f32_dpp v92, v92, v92 quad_perm:[1,0,3,2] row_mask:0xf bank_mask:0xf bound_ctrl:1
	ds_read_b32 v78, v85 offset:36224
	s_nop 0
	v_add_f32_dpp v92, v92, v92 quad_perm:[2,3,0,1] row_mask:0xf bank_mask:0xf bound_ctrl:1
	s_nop 1
	v_add_f32_dpp v92, v92, v92 row_half_mirror row_mask:0xf bank_mask:0xf bound_ctrl:1
	v_add_f32_e32 v103, v94, v95
	v_cndmask_b32_e64 v58, v99, v103, s[6:7]
	v_add_f32_dpp v92, v92, v92 row_mirror row_mask:0xf bank_mask:0xf bound_ctrl:1
	v_cndmask_b32_e64 v39, v103, v99, s[6:7]
	v_pk_fma_f32 v[0:1], v[8:9], v[92:93], v[86:87] op_sel_hi:[1,0,1]
	v_pk_fma_f32 v[2:3], v[10:11], v[92:93], v[88:89] op_sel_hi:[1,0,1]
	v_add_f32_dpp v39, v58, v39 quad_perm:[1,0,3,2] row_mask:0xf bank_mask:0xf bound_ctrl:1
	v_cndmask_b32_e64 v59, v36, v38, s[8:9]
	v_cndmask_b32_e64 v56, v38, v36, s[8:9]
	s_nop 1
	v_add_f32_dpp v56, v59, v56 quad_perm:[2,3,0,1] row_mask:0xf bank_mask:0xf bound_ctrl:1
	s_waitcnt lgkmcnt(5)
	v_pk_mul_f32 v[90:91], v[0:1], v[24:25]
	v_pk_fma_f32 v[86:87], v[32:33], v[76:77], v[0:1] op_sel_hi:[1,0,1]
	v_pk_fma_f32 v[90:91], v[2:3], v[26:27], v[90:91]
	v_pk_mul_f32 v[94:95], v[0:1], v[20:21]
	v_pk_fma_f32 v[88:89], v[34:35], v[76:77], v[2:3] op_sel_hi:[1,0,1]
	v_add_f32_e32 v92, v90, v91
	v_pk_fma_f32 v[94:95], v[2:3], v[22:23], v[94:95]
	ds_read_b128 v[4:7], v67 offset:36288
	v_add_f32_dpp v92, v92, v92 quad_perm:[1,0,3,2] row_mask:0xf bank_mask:0xf bound_ctrl:1
	ds_read_b128 v[12:15], v67 offset:36800
	ds_read_b128 v[8:11], v67 offset:36544
	v_add_f32_dpp v92, v92, v92 quad_perm:[2,3,0,1] row_mask:0xf bank_mask:0xf bound_ctrl:1
	ds_read_b128 v[20:23], v67 offset:37312
	ds_read_b32 v74, v85 offset:37568
	v_add_f32_dpp v92, v92, v92 row_half_mirror row_mask:0xf bank_mask:0xf bound_ctrl:1
	v_add_f32_e32 v96, v94, v95
	v_cndmask_b32_e64 v59, v37, v39, s[8:9]
	v_add_f32_dpp v92, v92, v92 row_mirror row_mask:0xf bank_mask:0xf bound_ctrl:1
	v_cndmask_b32_e64 v57, v39, v37, s[8:9]
	v_pk_fma_f32 v[0:1], v[28:29], v[92:93], v[86:87] op_sel_hi:[1,0,1]
	v_pk_fma_f32 v[2:3], v[30:31], v[92:93], v[88:89] op_sel_hi:[1,0,1]
	v_add_f32_dpp v57, v59, v57 quad_perm:[2,3,0,1] row_mask:0xf bank_mask:0xf bound_ctrl:1
	v_add_f32_dpp v56, v56, v56 row_ror:4 row_mask:0xf bank_mask:0xf bound_ctrl:1
	s_waitcnt lgkmcnt(5)
	v_pk_mul_f32 v[90:91], v[0:1], v[44:45]
	v_pk_fma_f32 v[86:87], v[52:53], v[78:79], v[0:1] op_sel_hi:[1,0,1]
	v_pk_fma_f32 v[90:91], v[2:3], v[46:47], v[90:91]
	v_pk_mul_f32 v[94:95], v[0:1], v[40:41]
	v_pk_fma_f32 v[88:89], v[54:55], v[78:79], v[2:3] op_sel_hi:[1,0,1]
	v_add_f32_e32 v92, v90, v91
	v_pk_fma_f32 v[94:95], v[2:3], v[42:43], v[94:95]
	ds_read_b128 v[24:27], v67 offset:37632
	v_add_f32_dpp v92, v92, v92 quad_perm:[1,0,3,2] row_mask:0xf bank_mask:0xf bound_ctrl:1
	ds_read_b128 v[32:35], v67 offset:38144
	ds_read_b128 v[28:31], v67 offset:37888
	v_add_f32_dpp v92, v92, v92 quad_perm:[2,3,0,1] row_mask:0xf bank_mask:0xf bound_ctrl:1
	ds_read_b128 v[40:43], v67 offset:38656
	ds_read_b32 v76, v85 offset:38912
	v_add_f32_dpp v92, v92, v92 row_half_mirror row_mask:0xf bank_mask:0xf bound_ctrl:1
	v_add_f32_e32 v97, v94, v95
	v_add_f32_dpp v56, v56, v56 row_ror:8 row_mask:0xf bank_mask:0xf bound_ctrl:1
	v_add_f32_dpp v92, v92, v92 row_mirror row_mask:0xf bank_mask:0xf bound_ctrl:1
	v_add_f32_dpp v57, v57, v57 row_ror:4 row_mask:0xf bank_mask:0xf bound_ctrl:1
	v_pk_fma_f32 v[0:1], v[48:49], v[92:93], v[86:87] op_sel_hi:[1,0,1]
	v_pk_fma_f32 v[2:3], v[50:51], v[92:93], v[88:89] op_sel_hi:[1,0,1]
	v_add_f32_dpp v57, v57, v57 row_ror:8 row_mask:0xf bank_mask:0xf bound_ctrl:1
	s_waitcnt lgkmcnt(5)
	v_pk_mul_f32 v[90:91], v[0:1], v[4:5]
	v_pk_fma_f32 v[86:87], v[12:13], v[74:75], v[0:1] op_sel_hi:[1,0,1]
	v_pk_fma_f32 v[90:91], v[2:3], v[6:7], v[90:91]
	v_pk_mul_f32 v[94:95], v[0:1], v[80:81]
	v_pk_fma_f32 v[88:89], v[14:15], v[74:75], v[2:3] op_sel_hi:[1,0,1]
	v_add_f32_e32 v92, v90, v91
	v_pk_fma_f32 v[94:95], v[2:3], v[82:83], v[94:95]
	ds_read_b128 v[44:47], v67 offset:38976
	v_add_f32_dpp v92, v92, v92 quad_perm:[1,0,3,2] row_mask:0xf bank_mask:0xf bound_ctrl:1
	ds_read_b128 v[52:55], v67 offset:39488
	ds_read_b128 v[48:51], v67 offset:39232
	v_add_f32_dpp v92, v92, v92 quad_perm:[2,3,0,1] row_mask:0xf bank_mask:0xf bound_ctrl:1
	ds_read_b128 v[80:83], v67 offset:40000
	ds_read_b32 v78, v85 offset:40256
	v_add_f32_dpp v92, v92, v92 row_half_mirror row_mask:0xf bank_mask:0xf bound_ctrl:1
	v_add_f32_e32 v98, v94, v95
	v_mov_b32_dpp v56, v57 quad_perm:[0,1,2,3] row_mask:0xf bank_mask:0x2
	v_add_f32_dpp v92, v92, v92 row_mirror row_mask:0xf bank_mask:0xf bound_ctrl:1
	v_cvt_pk_bf16_f32 v56, v56, v56
	v_pk_fma_f32 v[0:1], v[8:9], v[92:93], v[86:87] op_sel_hi:[1,0,1]
	v_pk_fma_f32 v[2:3], v[10:11], v[92:93], v[88:89] op_sel_hi:[1,0,1]
	s_and_saveexec_b64 s[16:17], s[58:59]
	global_store_short v[72:73], v56, off
	s_or_b64 exec, exec, s[16:17]
	v_lshl_add_u64 v[72:73], s[14:15], 1, v[72:73]
	s_waitcnt lgkmcnt(5)
	v_pk_mul_f32 v[90:91], v[0:1], v[24:25]
	v_pk_fma_f32 v[86:87], v[32:33], v[76:77], v[0:1] op_sel_hi:[1,0,1]
	v_pk_fma_f32 v[90:91], v[2:3], v[26:27], v[90:91]
	v_pk_mul_f32 v[94:95], v[0:1], v[20:21]
	v_pk_fma_f32 v[88:89], v[34:35], v[76:77], v[2:3] op_sel_hi:[1,0,1]
	v_add_f32_e32 v92, v90, v91
	v_pk_fma_f32 v[94:95], v[2:3], v[22:23], v[94:95]
	ds_read_b128 v[4:7], v67 offset:40320
	v_add_f32_dpp v92, v92, v92 quad_perm:[1,0,3,2] row_mask:0xf bank_mask:0xf bound_ctrl:1
	ds_read_b128 v[12:15], v67 offset:40832
	ds_read_b128 v[8:11], v67 offset:40576
	v_add_f32_dpp v92, v92, v92 quad_perm:[2,3,0,1] row_mask:0xf bank_mask:0xf bound_ctrl:1
	ds_read_b128 v[20:23], v67 offset:41344
	ds_read_b32 v74, v85 offset:41600
	v_add_f32_dpp v92, v92, v92 row_half_mirror row_mask:0xf bank_mask:0xf bound_ctrl:1
	v_add_f32_e32 v99, v94, v95
	s_nop 0
	v_add_f32_dpp v92, v92, v92 row_mirror row_mask:0xf bank_mask:0xf bound_ctrl:1
	v_pk_fma_f32 v[0:1], v[28:29], v[92:93], v[86:87] op_sel_hi:[1,0,1]
	v_pk_fma_f32 v[2:3], v[30:31], v[92:93], v[88:89] op_sel_hi:[1,0,1]
	s_waitcnt lgkmcnt(5)
	v_pk_mul_f32 v[90:91], v[0:1], v[44:45]
	v_pk_fma_f32 v[86:87], v[52:53], v[78:79], v[0:1] op_sel_hi:[1,0,1]
	v_pk_fma_f32 v[90:91], v[2:3], v[46:47], v[90:91]
	v_pk_mul_f32 v[94:95], v[0:1], v[40:41]
	v_pk_fma_f32 v[88:89], v[54:55], v[78:79], v[2:3] op_sel_hi:[1,0,1]
	v_add_f32_e32 v92, v90, v91
	v_pk_fma_f32 v[94:95], v[2:3], v[42:43], v[94:95]
	ds_read_b128 v[24:27], v67 offset:41664
	v_add_f32_dpp v92, v92, v92 quad_perm:[1,0,3,2] row_mask:0xf bank_mask:0xf bound_ctrl:1
	ds_read_b128 v[32:35], v67 offset:42176
	ds_read_b128 v[28:31], v67 offset:41920
	v_add_f32_dpp v92, v92, v92 quad_perm:[2,3,0,1] row_mask:0xf bank_mask:0xf bound_ctrl:1
	ds_read_b128 v[40:43], v67 offset:42688
	ds_read_b32 v76, v85 offset:42944
	v_add_f32_dpp v92, v92, v92 row_half_mirror row_mask:0xf bank_mask:0xf bound_ctrl:1
	v_add_f32_e32 v100, v94, v95
	ds_read_b128 v[16:19], v67 offset:42432
	v_add_f32_dpp v92, v92, v92 row_mirror row_mask:0xf bank_mask:0xf bound_ctrl:1
	v_cndmask_b32_e64 v58, v96, v100, s[6:7]
	v_pk_fma_f32 v[0:1], v[48:49], v[92:93], v[86:87] op_sel_hi:[1,0,1]
	v_pk_fma_f32 v[2:3], v[50:51], v[92:93], v[88:89] op_sel_hi:[1,0,1]
	v_cndmask_b32_e64 v36, v100, v96, s[6:7]
	s_nop 1
	v_add_f32_dpp v36, v58, v36 quad_perm:[1,0,3,2] row_mask:0xf bank_mask:0xf bound_ctrl:1
	s_waitcnt lgkmcnt(6)
	v_pk_mul_f32 v[90:91], v[0:1], v[4:5]
	v_pk_fma_f32 v[86:87], v[12:13], v[74:75], v[0:1] op_sel_hi:[1,0,1]
	v_pk_fma_f32 v[90:91], v[2:3], v[6:7], v[90:91]
	v_pk_mul_f32 v[94:95], v[0:1], v[80:81]
	v_pk_fma_f32 v[88:89], v[14:15], v[74:75], v[2:3] op_sel_hi:[1,0,1]
	v_add_f32_e32 v92, v90, v91
	v_pk_fma_f32 v[94:95], v[2:3], v[82:83], v[94:95]
	s_nop 0
	v_add_f32_dpp v92, v92, v92 quad_perm:[1,0,3,2] row_mask:0xf bank_mask:0xf bound_ctrl:1
	s_nop 1
	v_add_f32_dpp v92, v92, v92 quad_perm:[2,3,0,1] row_mask:0xf bank_mask:0xf bound_ctrl:1
	s_nop 1
	v_add_f32_dpp v92, v92, v92 row_half_mirror row_mask:0xf bank_mask:0xf bound_ctrl:1
	v_add_f32_e32 v101, v94, v95
	v_cndmask_b32_e64 v58, v97, v101, s[6:7]
	v_add_f32_dpp v92, v92, v92 row_mirror row_mask:0xf bank_mask:0xf bound_ctrl:1
	v_cndmask_b32_e64 v37, v101, v97, s[6:7]
	v_pk_fma_f32 v[0:1], v[8:9], v[92:93], v[86:87] op_sel_hi:[1,0,1]
	v_pk_fma_f32 v[2:3], v[10:11], v[92:93], v[88:89] op_sel_hi:[1,0,1]
	v_add_f32_dpp v37, v58, v37 quad_perm:[1,0,3,2] row_mask:0xf bank_mask:0xf bound_ctrl:1
	s_waitcnt lgkmcnt(0)
	v_pk_mul_f32 v[90:91], v[0:1], v[24:25]
	v_pk_fma_f32 v[86:87], v[32:33], v[76:77], v[0:1] op_sel_hi:[1,0,1]
	v_pk_fma_f32 v[90:91], v[2:3], v[26:27], v[90:91]
	v_pk_mul_f32 v[94:95], v[0:1], v[20:21]
	v_pk_fma_f32 v[88:89], v[34:35], v[76:77], v[2:3] op_sel_hi:[1,0,1]
	v_add_f32_e32 v92, v90, v91
	v_pk_fma_f32 v[94:95], v[2:3], v[22:23], v[94:95]
	s_nop 0
	v_add_f32_dpp v92, v92, v92 quad_perm:[1,0,3,2] row_mask:0xf bank_mask:0xf bound_ctrl:1
	s_nop 1
	v_add_f32_dpp v92, v92, v92 quad_perm:[2,3,0,1] row_mask:0xf bank_mask:0xf bound_ctrl:1
	s_nop 1
	v_add_f32_dpp v92, v92, v92 row_half_mirror row_mask:0xf bank_mask:0xf bound_ctrl:1
	v_add_f32_e32 v102, v94, v95
	v_cndmask_b32_e64 v58, v98, v102, s[6:7]
	v_add_f32_dpp v92, v92, v92 row_mirror row_mask:0xf bank_mask:0xf bound_ctrl:1
	v_cndmask_b32_e64 v38, v102, v98, s[6:7]
	v_pk_fma_f32 v[0:1], v[28:29], v[92:93], v[86:87] op_sel_hi:[1,0,1]
	v_pk_fma_f32 v[2:3], v[30:31], v[92:93], v[88:89] op_sel_hi:[1,0,1]
	v_add_f32_dpp v38, v58, v38 quad_perm:[1,0,3,2] row_mask:0xf bank_mask:0xf bound_ctrl:1
	v_pk_mul_f32 v[94:95], v[0:1], v[40:41]
	v_pk_fma_f32 v[94:95], v[2:3], v[42:43], v[94:95]
	v_pk_mul_f32 v[0:1], v[0:1], v[16:17]
	v_pk_mul_f32 v[2:3], v[2:3], v[18:19]
	v_add_f32_e32 v103, v94, v95
	v_cndmask_b32_e64 v58, v99, v103, s[6:7]
	v_cndmask_b32_e64 v39, v103, v99, s[6:7]
	s_nop 1
	v_add_f32_dpp v39, v58, v39 quad_perm:[1,0,3,2] row_mask:0xf bank_mask:0xf bound_ctrl:1
	v_cndmask_b32_e64 v59, v36, v38, s[8:9]
	v_cndmask_b32_e64 v56, v38, v36, s[8:9]
	s_nop 1
	v_add_f32_dpp v56, v59, v56 quad_perm:[2,3,0,1] row_mask:0xf bank_mask:0xf bound_ctrl:1
	v_cndmask_b32_e64 v59, v37, v39, s[8:9]
	v_cndmask_b32_e64 v57, v39, v37, s[8:9]
	s_nop 1
	v_add_f32_dpp v57, v59, v57 quad_perm:[2,3,0,1] row_mask:0xf bank_mask:0xf bound_ctrl:1
	v_add_f32_dpp v56, v56, v56 row_ror:4 row_mask:0xf bank_mask:0xf bound_ctrl:1
	s_nop 1
	v_add_f32_dpp v56, v56, v56 row_ror:8 row_mask:0xf bank_mask:0xf bound_ctrl:1
	v_add_f32_dpp v57, v57, v57 row_ror:4 row_mask:0xf bank_mask:0xf bound_ctrl:1
	s_nop 1
	v_add_f32_dpp v57, v57, v57 row_ror:8 row_mask:0xf bank_mask:0xf bound_ctrl:1
	s_nop 1
	v_mov_b32_dpp v56, v57 quad_perm:[0,1,2,3] row_mask:0xf bank_mask:0x2
	v_cvt_pk_bf16_f32 v56, v56, v56
	s_and_saveexec_b64 s[16:17], s[58:59]
	global_store_short v[72:73], v56, off
	s_or_b64 exec, exec, s[16:17]
	v_lshl_add_u64 v[72:73], s[14:15], 1, v[72:73]
	s_branch .LBB0_1334
